# NSA selected-pass cross-half max/sum via v_permlane32_swap instead of ds_bpermute (on top of DPP ss reduce in GEMM epilogue)
# baseline (speedup 1.0000x reference)
; DI float shx_(float v, int m) { return __int_as_float(__builtin_amdgcn_ds_bpermute((lane_pinned_() ^ m) << 2, __float_as_int(v))); }
; DI int shx_(int v, int m) { return __builtin_amdgcn_ds_bpermute((lane_pinned_() ^ m) << 2, v); }
; template <int MODE> ...
;     ...
;         float mr = fmaxf(fmaxf(acc[0], acc[1]), fmaxf(acc[2], acc[3]));
; #pragma unroll
;         for (int i = 4; i < 16; i += 2) mr = fmaxf(mr, fmaxf(acc[i], acc[i + 1]));
;         float mx = fmaxf(m, mr * C);
;         if (MODE == 2) mx = bit ? mx : m;
;         mx = fmaxf(mx, shx_(mx, 32));
;         if (MODE >= 2) mx = (mx > m + 8.f) ? mx : m;
;         if (MODE == 0) { l *= __builtin_amdgcn_exp2f(m - mx); }
;         else if (__any(mx > m)) {
;           const float alpha = __builtin_amdgcn_exp2f(m - mx);
;           l *= alpha;
; #pragma unroll
;           for (int et = 0; et < 4; ++et)
; #pragma unroll
;             for (int i = 0; i < 16; ++i) o[et][i] *= alpha;
;         }
;         m = mx;
;         const float moff = ((MODE == 2 && !bit) || m < -1e29f) ? 1e30f : m;
;         float rs = 0.f;
; #pragma unroll
;         for (int i = 0; i < 16; ++i) {
;           const float pp = __builtin_amdgcn_exp2f(__builtin_fmaf(acc[i], C, -moff));
;           acc[i] = pp; rs += pp;
;         }
;         rs += shx_(rs, 32);
;         l += rs;
;       }
;       if (NEEDV) {
;         bf16x8 p0 = packf(acc, 0), p1 = packf(acc, 1);
;         pv_lds(Vs, half, p0, p1, o, r, h);
.LBB0_166:
	s_or_b64 exec, exec, s[2:3]
	ds_read2_b64 v[242:245], v188 offset1:2
	ds_read2_b64 v[246:249], v188 offset0:4 offset1:6
	s_nop 8
	v_max_f32_e32 v200, v69, v69
	v_max_f32_e32 v202, v68, v68
	v_max_f32_e32 v200, v202, v200
	v_max_f32_e32 v202, v71, v71
	v_max_f32_e32 v203, v70, v70
	v_max_f32_e32 v202, v203, v202
	v_max_f32_e32 v203, v73, v73
	v_max_f32_e32 v214, v72, v72
	v_max3_f32 v200, v66, v67, v200
	v_max_f32_e32 v203, v214, v203
	v_max3_f32 v200, v200, v202, v203
	v_max_f32_e32 v202, v75, v75
	v_max_f32_e32 v203, v74, v74
	v_max_f32_e32 v202, v203, v202
	v_max_f32_e32 v203, v77, v77
	v_max_f32_e32 v214, v76, v76
	v_max_f32_e32 v203, v214, v203
	v_max3_f32 v200, v200, v202, v203
	v_max_f32_e32 v202, v79, v79
	v_max_f32_e32 v203, v78, v78
	v_max_f32_e32 v202, v203, v202
	v_max_f32_e32 v203, v81, v81
	v_max_f32_e32 v214, v80, v80
	v_max_f32_e32 v203, v214, v203
	v_max3_f32 v200, v200, v202, v203
	v_mul_f32_e32 v200, 0x3e0293ee, v200
	v_max_f32_e32 v202, v166, v166
	v_max_f32_e32 v200, v202, v200
	v_cndmask_b32_e64 v200, v166, v200, s[0:1]
	v_mov_b32_e32 v202, v200
	s_nop 1
	v_permlane32_swap_b32 v202, v200
	v_max_f32_e32 v200, v200, v200
	s_waitcnt lgkmcnt(0)
	v_max_f32_e32 v202, v202, v202
	v_max_f32_e32 v200, v200, v202
	v_add_f32_e32 v202, 0x41000000, v166
	v_cmp_gt_f32_e32 vcc, v200, v202
	s_nop 1
	v_cndmask_b32_e32 v200, v166, v200, vcc
	v_cmp_gt_f32_e32 vcc, v200, v166
	s_cbranch_vccz .LBB0_168
	v_sub_f32_e32 v166, v166, v200
	v_exp_f32_e32 v166, v166
	s_nop 0
	v_mul_f32_e32 v167, v167, v166
	v_pk_mul_f32 v[64:65], v[64:65], v[166:167] op_sel_hi:[1,0]
	v_pk_mul_f32 v[62:63], v[62:63], v[166:167] op_sel_hi:[1,0]
	v_pk_mul_f32 v[60:61], v[60:61], v[166:167] op_sel_hi:[1,0]
	v_pk_mul_f32 v[58:59], v[58:59], v[166:167] op_sel_hi:[1,0]
	v_pk_mul_f32 v[56:57], v[56:57], v[166:167] op_sel_hi:[1,0]
	v_pk_mul_f32 v[54:55], v[54:55], v[166:167] op_sel_hi:[1,0]
	v_pk_mul_f32 v[52:53], v[52:53], v[166:167] op_sel_hi:[1,0]
	v_pk_mul_f32 v[50:51], v[50:51], v[166:167] op_sel_hi:[1,0]
	v_pk_mul_f32 v[48:49], v[48:49], v[166:167] op_sel_hi:[1,0]
	v_pk_mul_f32 v[46:47], v[46:47], v[166:167] op_sel_hi:[1,0]
	v_pk_mul_f32 v[44:45], v[44:45], v[166:167] op_sel_hi:[1,0]
	v_pk_mul_f32 v[42:43], v[42:43], v[166:167] op_sel_hi:[1,0]
	v_pk_mul_f32 v[40:41], v[40:41], v[166:167] op_sel_hi:[1,0]
	v_pk_mul_f32 v[38:39], v[38:39], v[166:167] op_sel_hi:[1,0]
	v_pk_mul_f32 v[36:37], v[36:37], v[166:167] op_sel_hi:[1,0]
	v_pk_mul_f32 v[34:35], v[34:35], v[166:167] op_sel_hi:[1,0]
	v_pk_mul_f32 v[32:33], v[32:33], v[166:167] op_sel_hi:[1,0]
	v_pk_mul_f32 v[30:31], v[30:31], v[166:167] op_sel_hi:[1,0]
	v_pk_mul_f32 v[28:29], v[28:29], v[166:167] op_sel_hi:[1,0]
	v_pk_mul_f32 v[26:27], v[26:27], v[166:167] op_sel_hi:[1,0]
	v_pk_mul_f32 v[24:25], v[24:25], v[166:167] op_sel_hi:[1,0]
	v_pk_mul_f32 v[22:23], v[22:23], v[166:167] op_sel_hi:[1,0]
	v_pk_mul_f32 v[20:21], v[20:21], v[166:167] op_sel_hi:[1,0]
	v_pk_mul_f32 v[18:19], v[18:19], v[166:167] op_sel_hi:[1,0]
	v_pk_mul_f32 v[16:17], v[16:17], v[166:167] op_sel_hi:[1,0]
	v_pk_mul_f32 v[14:15], v[14:15], v[166:167] op_sel_hi:[1,0]
	v_pk_mul_f32 v[12:13], v[12:13], v[166:167] op_sel_hi:[1,0]
	v_pk_mul_f32 v[10:11], v[10:11], v[166:167] op_sel_hi:[1,0]
	v_pk_mul_f32 v[8:9], v[8:9], v[166:167] op_sel_hi:[1,0]
	v_pk_mul_f32 v[6:7], v[6:7], v[166:167] op_sel_hi:[1,0]
	v_pk_mul_f32 v[4:5], v[4:5], v[166:167] op_sel_hi:[1,0]
	v_pk_mul_f32 v[2:3], v[2:3], v[166:167] op_sel_hi:[1,0]
.LBB0_168:
	v_cmp_ngt_f32_e32 vcc, s45, v200
	s_and_b64 s[0:1], s[0:1], vcc
	v_cndmask_b32_e64 v166, v209, -v200, s[0:1]
	v_fmamk_f32 v66, v66, 0x3e0293ee, v166
	v_exp_f32_e32 v66, v66
	v_fmamk_f32 v67, v67, 0x3e0293ee, v166
	v_exp_f32_e32 v67, v67
	v_fmamk_f32 v68, v68, 0x3e0293ee, v166
	v_exp_f32_e32 v68, v68
	v_fmamk_f32 v69, v69, 0x3e0293ee, v166
	v_exp_f32_e32 v69, v69
	v_fmamk_f32 v70, v70, 0x3e0293ee, v166
	v_add_f32_e32 v202, 0, v66
	v_exp_f32_e32 v203, v70
	v_add_f32_e32 v202, v67, v202
	v_add_f32_e32 v202, v68, v202
	v_add_f32_e32 v202, v69, v202
	v_fmamk_f32 v71, v71, 0x3e0293ee, v166
	v_add_f32_e32 v70, v203, v202
	v_exp_f32_e32 v202, v71
	v_fmamk_f32 v71, v72, 0x3e0293ee, v166
	v_exp_f32_e32 v214, v71
	v_fmamk_f32 v71, v73, 0x3e0293ee, v166
	v_exp_f32_e32 v73, v71
	v_fmamk_f32 v71, v74, 0x3e0293ee, v166
	v_exp_f32_e32 v74, v71
	v_fmamk_f32 v71, v75, 0x3e0293ee, v166
	v_add_f32_e32 v70, v202, v70
	v_exp_f32_e32 v75, v71
	v_fmamk_f32 v71, v76, 0x3e0293ee, v166
	v_add_f32_e32 v70, v214, v70
	v_exp_f32_e32 v76, v71
	v_fmamk_f32 v71, v77, 0x3e0293ee, v166
	v_add_f32_e32 v70, v73, v70
	v_exp_f32_e32 v77, v71
	v_fmamk_f32 v71, v78, 0x3e0293ee, v166
	v_add_f32_e32 v70, v74, v70
	v_exp_f32_e32 v78, v71
	v_fmamk_f32 v71, v79, 0x3e0293ee, v166
	v_add_f32_e32 v70, v75, v70
	v_exp_f32_e32 v79, v71
	v_fmamk_f32 v71, v80, 0x3e0293ee, v166
	v_add_f32_e32 v70, v76, v70
	v_exp_f32_e32 v80, v71
	v_fmac_f32_e32 v166, 0x3e0293ee, v81
	v_add_f32_e32 v70, v77, v70
	v_exp_f32_e32 v81, v166
	v_add_f32_e32 v70, v78, v70
	v_add_f32_e32 v70, v79, v70
	v_add_f32_e32 v70, v80, v70
	v_add_f32_e32 v70, v81, v70
	v_mov_b32_e32 v71, v70
	s_nop 1
	v_permlane32_swap_b32 v71, v70
	v_cvt_pk_bf16_f32 v72, v203, v202
	v_cvt_pk_bf16_f32 v73, v214, v73
	s_waitcnt lgkmcnt(0)
	v_add_f32_e32 v70, v70, v71
	v_add_f32_e32 v167, v167, v70
	v_cvt_pk_bf16_f32 v70, v66, v67
	v_cvt_pk_bf16_f32 v71, v68, v69
	v_cvt_pk_bf16_f32 v66, v74, v75
	v_cvt_pk_bf16_f32 v67, v76, v77
	v_cvt_pk_bf16_f32 v68, v78, v79
	v_cvt_pk_bf16_f32 v69, v80, v81
	ds_read2_b64 v[74:77], v193 offset0:64 offset1:66
	ds_read2_b64 v[78:81], v193 offset0:68 offset1:70
	s_waitcnt lgkmcnt(3)
	v_mfma_f32_32x32x16_bf16 v[50:65], v[242:245], v[70:73], v[50:65]
	s_waitcnt lgkmcnt(2)
	v_mfma_f32_32x32x16_bf16 v[50:65], v[246:249], v[66:69], v[50:65]
	ds_read2_b64 v[242:245], v194 offset0:128 offset1:130
	ds_read2_b64 v[246:249], v194 offset0:132 offset1:134
	s_waitcnt lgkmcnt(3)
	v_mfma_f32_32x32x16_bf16 v[34:49], v[74:77], v[70:73], v[34:49]
	s_waitcnt lgkmcnt(2)
	v_mfma_f32_32x32x16_bf16 v[34:49], v[78:81], v[66:69], v[34:49]
	ds_read2_b64 v[74:77], v195 offset0:192 offset1:194
	ds_read2_b64 v[78:81], v195 offset0:196 offset1:198
	s_waitcnt lgkmcnt(3)
	v_mfma_f32_32x32x16_bf16 v[18:33], v[242:245], v[70:73], v[18:33]
	s_waitcnt lgkmcnt(2)
	v_mfma_f32_32x32x16_bf16 v[18:33], v[246:249], v[66:69], v[18:33]
	s_waitcnt lgkmcnt(1)
	v_mfma_f32_32x32x16_bf16 v[2:17], v[74:77], v[70:73], v[2:17]
	s_waitcnt lgkmcnt(0)
	v_mfma_f32_32x32x16_bf16 v[2:17], v[78:81], v[66:69], v[2:17]
	s_cmp_lt_u32 s11, s12
	s_cselect_b64 s[0:1], -1, 0
	s_cmp_ge_u32 s11, s12
	s_cbranch_scc1 .LBB0_170

; DI float shx_(float v, int m) { return __int_as_float(__builtin_amdgcn_ds_bpermute((lane_pinned_() ^ m) << 2, __float_as_int(v))); }
; DI int shx_(int v, int m) { return __builtin_amdgcn_ds_bpermute((lane_pinned_() ^ m) << 2, v); }
; template <int MODE> ...
;     ...
;         float mr = fmaxf(fmaxf(acc[0], acc[1]), fmaxf(acc[2], acc[3]));
; #pragma unroll
;         for (int i = 4; i < 16; i += 2) mr = fmaxf(mr, fmaxf(acc[i], acc[i + 1]));
;         float mx = fmaxf(m, mr * C);
;         if (MODE == 2) mx = bit ? mx : m;
;         mx = fmaxf(mx, shx_(mx, 32));
;         if (MODE >= 2) mx = (mx > m + 8.f) ? mx : m;
;         if (MODE == 0) { l *= __builtin_amdgcn_exp2f(m - mx); }
;         else if (__any(mx > m)) {
;           const float alpha = __builtin_amdgcn_exp2f(m - mx);
;           l *= alpha;
; #pragma unroll
;           for (int et = 0; et < 4; ++et)
; #pragma unroll
;             for (int i = 0; i < 16; ++i) o[et][i] *= alpha;
;         }
;         m = mx;
;         const float moff = ((MODE == 2 && !bit) || m < -1e29f) ? 1e30f : m;
;         float rs = 0.f;
; #pragma unroll
;         for (int i = 0; i < 16; ++i) {
;           const float pp = __builtin_amdgcn_exp2f(__builtin_fmaf(acc[i], C, -moff));
;           acc[i] = pp; rs += pp;
;         }
;         rs += shx_(rs, 32);
;         l += rs;
;       }
;       if (NEEDV) {
;         bf16x8 p0 = packf(acc, 0), p1 = packf(acc, 1);
;         pv_lds(Vs, half, p0, p1, o, r, h);
.LBB0_176:
	s_or_b64 exec, exec, s[2:3]
	v_add_u32_e32 v215, v187, v186
	v_add_u32_e32 v216, 0x2000, v215
	v_add_u32_e32 v217, 0x3000, v215
	ds_read2_b64 v[242:245], v215 offset1:2
	ds_read2_b64 v[246:249], v215 offset0:4 offset1:6
	s_nop 8
	v_max_f32_e32 v166, v69, v69
	v_max_f32_e32 v201, v68, v68
	v_max_f32_e32 v166, v201, v166
	v_max_f32_e32 v201, v71, v71
	v_max_f32_e32 v202, v70, v70
	v_max_f32_e32 v201, v202, v201
	v_max_f32_e32 v202, v73, v73
	v_max_f32_e32 v203, v72, v72
	v_max3_f32 v166, v66, v67, v166
	v_max_f32_e32 v202, v203, v202
	v_max3_f32 v166, v166, v201, v202
	v_max_f32_e32 v201, v75, v75
	v_max_f32_e32 v202, v74, v74
	v_max_f32_e32 v201, v202, v201
	v_max_f32_e32 v202, v77, v77
	v_max_f32_e32 v203, v76, v76
	v_max_f32_e32 v202, v203, v202
	v_max3_f32 v166, v166, v201, v202
	v_max_f32_e32 v201, v79, v79
	v_max_f32_e32 v202, v78, v78
	v_max_f32_e32 v201, v202, v201
	v_max_f32_e32 v202, v81, v81
	v_max_f32_e32 v203, v80, v80
	v_max_f32_e32 v202, v203, v202
	v_max3_f32 v166, v166, v201, v202
	v_mul_f32_e32 v166, 0x3e0293ee, v166
	v_max_f32_e32 v201, v200, v200
	v_max_f32_e32 v166, v201, v166
	v_cndmask_b32_e64 v166, v200, v166, s[0:1]
	v_mov_b32_e32 v201, v166
	s_nop 1
	v_permlane32_swap_b32 v201, v166
	v_max_f32_e32 v166, v166, v166
	s_waitcnt lgkmcnt(0)
	v_max_f32_e32 v201, v201, v201
	v_max_f32_e32 v166, v166, v201
	v_add_f32_e32 v201, 0x41000000, v200
	v_cmp_gt_f32_e32 vcc, v166, v201
	s_nop 1
	v_cndmask_b32_e32 v166, v200, v166, vcc
	v_cmp_gt_f32_e32 vcc, v166, v200
	s_cbranch_vccz .LBB0_178
	v_sub_f32_e32 v200, v200, v166
	v_exp_f32_e32 v200, v200
	s_nop 0
	v_mul_f32_e32 v167, v167, v200
	v_pk_mul_f32 v[64:65], v[64:65], v[200:201] op_sel_hi:[1,0]
	v_pk_mul_f32 v[62:63], v[62:63], v[200:201] op_sel_hi:[1,0]
	v_pk_mul_f32 v[60:61], v[60:61], v[200:201] op_sel_hi:[1,0]
	v_pk_mul_f32 v[58:59], v[58:59], v[200:201] op_sel_hi:[1,0]
	v_pk_mul_f32 v[56:57], v[56:57], v[200:201] op_sel_hi:[1,0]
	v_pk_mul_f32 v[54:55], v[54:55], v[200:201] op_sel_hi:[1,0]
	v_pk_mul_f32 v[52:53], v[52:53], v[200:201] op_sel_hi:[1,0]
	v_pk_mul_f32 v[50:51], v[50:51], v[200:201] op_sel_hi:[1,0]
	v_pk_mul_f32 v[48:49], v[48:49], v[200:201] op_sel_hi:[1,0]
	v_pk_mul_f32 v[46:47], v[46:47], v[200:201] op_sel_hi:[1,0]
	v_pk_mul_f32 v[44:45], v[44:45], v[200:201] op_sel_hi:[1,0]
	v_pk_mul_f32 v[42:43], v[42:43], v[200:201] op_sel_hi:[1,0]
	v_pk_mul_f32 v[40:41], v[40:41], v[200:201] op_sel_hi:[1,0]
	v_pk_mul_f32 v[38:39], v[38:39], v[200:201] op_sel_hi:[1,0]
	v_pk_mul_f32 v[36:37], v[36:37], v[200:201] op_sel_hi:[1,0]
	v_pk_mul_f32 v[34:35], v[34:35], v[200:201] op_sel_hi:[1,0]
	v_pk_mul_f32 v[32:33], v[32:33], v[200:201] op_sel_hi:[1,0]
	v_pk_mul_f32 v[30:31], v[30:31], v[200:201] op_sel_hi:[1,0]
	v_pk_mul_f32 v[28:29], v[28:29], v[200:201] op_sel_hi:[1,0]
	v_pk_mul_f32 v[26:27], v[26:27], v[200:201] op_sel_hi:[1,0]
	v_pk_mul_f32 v[24:25], v[24:25], v[200:201] op_sel_hi:[1,0]
	v_pk_mul_f32 v[22:23], v[22:23], v[200:201] op_sel_hi:[1,0]
	v_pk_mul_f32 v[20:21], v[20:21], v[200:201] op_sel_hi:[1,0]
	v_pk_mul_f32 v[18:19], v[18:19], v[200:201] op_sel_hi:[1,0]
	v_pk_mul_f32 v[16:17], v[16:17], v[200:201] op_sel_hi:[1,0]
	v_pk_mul_f32 v[14:15], v[14:15], v[200:201] op_sel_hi:[1,0]
	v_pk_mul_f32 v[12:13], v[12:13], v[200:201] op_sel_hi:[1,0]
	v_pk_mul_f32 v[10:11], v[10:11], v[200:201] op_sel_hi:[1,0]
	v_pk_mul_f32 v[8:9], v[8:9], v[200:201] op_sel_hi:[1,0]
	v_pk_mul_f32 v[6:7], v[6:7], v[200:201] op_sel_hi:[1,0]
	v_pk_mul_f32 v[4:5], v[4:5], v[200:201] op_sel_hi:[1,0]
	v_pk_mul_f32 v[2:3], v[2:3], v[200:201] op_sel_hi:[1,0]
.LBB0_178:
	v_cmp_ngt_f32_e32 vcc, s45, v166
	s_and_b64 s[0:1], s[0:1], vcc
	v_cndmask_b32_e64 v200, v209, -v166, s[0:1]
	v_fmamk_f32 v66, v66, 0x3e0293ee, v200
	v_exp_f32_e32 v66, v66
	v_fmamk_f32 v67, v67, 0x3e0293ee, v200
	v_exp_f32_e32 v67, v67
	v_fmamk_f32 v68, v68, 0x3e0293ee, v200
	v_exp_f32_e32 v68, v68
	v_fmamk_f32 v69, v69, 0x3e0293ee, v200
	v_exp_f32_e32 v69, v69
	v_fmamk_f32 v70, v70, 0x3e0293ee, v200
	v_add_f32_e32 v201, 0, v66
	v_exp_f32_e32 v202, v70
	v_add_f32_e32 v201, v67, v201
	v_add_f32_e32 v201, v68, v201
	v_add_f32_e32 v201, v69, v201
	v_fmamk_f32 v71, v71, 0x3e0293ee, v200
	v_add_f32_e32 v70, v202, v201
	v_exp_f32_e32 v201, v71
	v_fmamk_f32 v71, v72, 0x3e0293ee, v200
	v_exp_f32_e32 v203, v71
	v_fmamk_f32 v71, v73, 0x3e0293ee, v200
	v_exp_f32_e32 v73, v71
	v_fmamk_f32 v71, v74, 0x3e0293ee, v200
	v_exp_f32_e32 v74, v71
	v_fmamk_f32 v71, v75, 0x3e0293ee, v200
	v_add_f32_e32 v70, v201, v70
	v_exp_f32_e32 v75, v71
	v_fmamk_f32 v71, v76, 0x3e0293ee, v200
	v_add_f32_e32 v70, v203, v70
	v_exp_f32_e32 v76, v71
	v_fmamk_f32 v71, v77, 0x3e0293ee, v200
	v_add_f32_e32 v70, v73, v70
	v_exp_f32_e32 v77, v71
	v_fmamk_f32 v71, v78, 0x3e0293ee, v200
	v_add_f32_e32 v70, v74, v70
	v_exp_f32_e32 v78, v71
	v_fmamk_f32 v71, v79, 0x3e0293ee, v200
	v_add_f32_e32 v70, v75, v70
	v_exp_f32_e32 v79, v71
	v_fmamk_f32 v71, v80, 0x3e0293ee, v200
	v_add_f32_e32 v70, v76, v70
	v_exp_f32_e32 v80, v71
	v_fmac_f32_e32 v200, 0x3e0293ee, v81
	v_add_f32_e32 v70, v77, v70
	v_exp_f32_e32 v81, v200
	v_add_f32_e32 v70, v78, v70
	v_add_f32_e32 v70, v79, v70
	v_add_f32_e32 v70, v80, v70
	v_add_f32_e32 v70, v81, v70
	v_mov_b32_e32 v71, v70
	s_nop 1
	v_permlane32_swap_b32 v71, v70
	v_cvt_pk_bf16_f32 v72, v202, v201
	v_cvt_pk_bf16_f32 v73, v203, v73
	s_waitcnt lgkmcnt(0)
	v_add_f32_e32 v70, v70, v71
	v_add_f32_e32 v167, v167, v70
	v_cvt_pk_bf16_f32 v70, v66, v67
	v_cvt_pk_bf16_f32 v71, v68, v69
	v_cvt_pk_bf16_f32 v66, v74, v75
	v_cvt_pk_bf16_f32 v67, v76, v77
	v_cvt_pk_bf16_f32 v68, v78, v79
	v_cvt_pk_bf16_f32 v69, v80, v81
	v_add_u32_e32 v78, 0x1000, v215
	ds_read2_b64 v[74:77], v78 offset0:64 offset1:66
	ds_read2_b64 v[78:81], v78 offset0:68 offset1:70
	s_waitcnt lgkmcnt(3)
	v_mfma_f32_32x32x16_bf16 v[50:65], v[242:245], v[70:73], v[50:65]
	s_waitcnt lgkmcnt(2)
	v_mfma_f32_32x32x16_bf16 v[50:65], v[246:249], v[66:69], v[50:65]
	ds_read2_b64 v[242:245], v216 offset0:128 offset1:130
	ds_read2_b64 v[246:249], v216 offset0:132 offset1:134
	s_waitcnt lgkmcnt(3)
	v_mfma_f32_32x32x16_bf16 v[34:49], v[74:77], v[70:73], v[34:49]
	s_waitcnt lgkmcnt(2)
	v_mfma_f32_32x32x16_bf16 v[34:49], v[78:81], v[66:69], v[34:49]
	ds_read2_b64 v[74:77], v217 offset0:192 offset1:194
	ds_read2_b64 v[78:81], v217 offset0:196 offset1:198
	s_waitcnt lgkmcnt(3)
	v_mfma_f32_32x32x16_bf16 v[18:33], v[242:245], v[70:73], v[18:33]
	s_waitcnt lgkmcnt(2)
	v_mfma_f32_32x32x16_bf16 v[18:33], v[246:249], v[66:69], v[18:33]
	s_waitcnt lgkmcnt(1)
	v_mfma_f32_32x32x16_bf16 v[2:17], v[74:77], v[70:73], v[2:17]
	s_waitcnt lgkmcnt(0)
	v_mfma_f32_32x32x16_bf16 v[2:17], v[78:81], v[66:69], v[2:17]
	s_mov_b64 s[0:1], 0x8000
	s_cmp_ge_u32 s8, s12
	s_cbranch_scc1 .LBB0_180

; DI unsigned pk2(float a, float b) { f32x2 v; v[0] = a; v[1] = b; return __builtin_bit_cast(unsigned, __builtin_convertvector(v, bf16v2)); }
; DI float shx_(float v, int m) { return __int_as_float(__builtin_amdgcn_ds_bpermute((lane_pinned_() ^ m) << 2, __float_as_int(v))); }
; DI int shx_(int v, int m) { return __builtin_amdgcn_ds_bpermute((lane_pinned_() ^ m) << 2, v); }
; DI void gemm_tile(const GD& g, int pm, int pn, bf16_t* shm) {
;     ...
;             if (g.gnext) {
;               u32x2 o2; o2[0] = pk2(x.x * gn.x, x.y * gn.y); o2[1] = pk2(x.z * gn.z, x.w * gn.w);
;               *reinterpret_cast<u32x2*>(g.hbout + (long)grow * DM + gcol) = o2;
;               float sq = (x.x * x.x + x.y * x.y) + (x.z * x.z + x.w * x.w);
;               sq += shx_(sq, 1); sq += shx_(sq, 2); sq += shx_(sq, 4); sq += shx_(sq, 8);
;               if ((lane & 15) == 0) g.ss[(long)grow * 32 + pn * 4 + wc] = sq;
.LBB0_625:
	v_mad_u64_u32 v[104:105], s[2:3], v96, s78, 0
	v_mov_b32_e32 v0, v105
	v_mad_u64_u32 v[106:107], s[2:3], v97, s78, v[0:1]
	v_mov_b32_e32 v105, v106
	v_lshl_add_u64 v[104:105], v[104:105], 2, s[34:35]
	s_waitcnt vmcnt(0) lgkmcnt(0)
	v_pk_add_f32 v[90:91], v[14:15], v[86:87]
	v_pk_add_f32 v[92:93], v[16:17], v[88:89]
	v_lshl_add_u64 v[104:105], v[94:95], 2, v[104:105]
	s_cmp_eq_u64 s[80:81], 0
	global_store_dwordx4 v[104:105], v[90:93], off
	s_cbranch_scc1 .LBB0_629
	v_pk_mul_f32 v[104:105], v[82:83], v[90:91]
	v_pk_mul_f32 v[106:107], v[84:85], v[92:93]
	v_cvt_pk_bf16_f32 v104, v104, v105
	v_cvt_pk_bf16_f32 v105, v106, v107
	v_lshlrev_b64 v[106:107], 12, v[96:97]
	v_pk_mul_f32 v[90:91], v[90:91], v[90:91]
	v_pk_mul_f32 v[92:93], v[92:93], v[92:93]
	v_lshl_add_u64 v[106:107], s[20:21], 0, v[106:107]
	v_add_f32_e32 v0, v92, v93
	v_add_f32_e32 v90, v90, v91
	v_lshl_add_u64 v[106:107], v[94:95], 1, v[106:107]
	v_add_f32_e32 v0, v90, v0
	global_store_dwordx2 v[106:107], v[104:105], off
	s_nop 1
	v_mov_b32_dpp v90, v0 quad_perm:[1,0,3,2] row_mask:0xf bank_mask:0xf
	s_waitcnt lgkmcnt(0)
	v_add_f32_e32 v0, v0, v90
	s_nop 1
	v_mov_b32_dpp v90, v0 quad_perm:[2,3,0,1] row_mask:0xf bank_mask:0xf
	s_waitcnt lgkmcnt(0)
	v_add_f32_e32 v0, v0, v90
	s_nop 1
	v_mov_b32_dpp v90, v0 row_half_mirror row_mask:0xf bank_mask:0xf
	s_waitcnt lgkmcnt(0)
	v_add_f32_e32 v90, v0, v90
	s_nop 1
	v_mov_b32_dpp v91, v90 row_ror:8 row_mask:0xf bank_mask:0xf
	s_and_saveexec_b64 s[2:3], s[4:5]
	s_cbranch_execz .LBB0_628
	v_lshlrev_b64 v[92:93], 7, v[96:97]
	v_lshl_add_u64 v[92:93], s[42:43], 0, v[92:93]
	v_lshl_add_u64 v[92:93], s[0:1], 2, v[92:93]
	v_lshlrev_b32_e32 v0, 2, v139
	v_lshl_add_u64 v[92:93], v[92:93], 0, v[0:1]
	s_waitcnt lgkmcnt(0)
	v_add_f32_e32 v0, v90, v91
	global_store_dword v[92:93], v0, off

; DI unsigned pk2(float a, float b) { f32x2 v; v[0] = a; v[1] = b; return __builtin_bit_cast(unsigned, __builtin_convertvector(v, bf16v2)); }
; DI float shx_(float v, int m) { return __int_as_float(__builtin_amdgcn_ds_bpermute((lane_pinned_() ^ m) << 2, __float_as_int(v))); }
; DI int shx_(int v, int m) { return __builtin_amdgcn_ds_bpermute((lane_pinned_() ^ m) << 2, v); }
; DI void gemm_tile(const GD& g, int pm, int pn, bf16_t* shm) {
;     ...
;             if (g.gnext) {
;               u32x2 o2; o2[0] = pk2(x.x * gn.x, x.y * gn.y); o2[1] = pk2(x.z * gn.z, x.w * gn.w);
;               *reinterpret_cast<u32x2*>(g.hbout + (long)grow * DM + gcol) = o2;
;               float sq = (x.x * x.x + x.y * x.y) + (x.z * x.z + x.w * x.w);
;               sq += shx_(sq, 1); sq += shx_(sq, 2); sq += shx_(sq, 4); sq += shx_(sq, 8);
;               if ((lane & 15) == 0) g.ss[(long)grow * 32 + pn * 4 + wc] = sq;
.LBB0_641:
	v_mad_u64_u32 v[104:105], s[2:3], v96, s78, 0
	v_mov_b32_e32 v0, v105
	v_mad_u64_u32 v[106:107], s[2:3], v97, s78, v[0:1]
	v_mov_b32_e32 v105, v106
	v_lshl_add_u64 v[104:105], v[104:105], 2, s[34:35]
	s_waitcnt lgkmcnt(0)
	v_pk_add_f32 v[90:91], v[6:7], v[86:87]
	v_pk_add_f32 v[92:93], v[8:9], v[88:89]
	v_lshl_add_u64 v[104:105], v[94:95], 2, v[104:105]
	s_cmp_eq_u64 s[80:81], 0
	global_store_dwordx4 v[104:105], v[90:93], off
	s_cbranch_scc1 .LBB0_645
	v_pk_mul_f32 v[104:105], v[82:83], v[90:91]
	v_pk_mul_f32 v[106:107], v[84:85], v[92:93]
	v_cvt_pk_bf16_f32 v104, v104, v105
	v_cvt_pk_bf16_f32 v105, v106, v107
	v_lshlrev_b64 v[106:107], 12, v[96:97]
	v_pk_mul_f32 v[90:91], v[90:91], v[90:91]
	v_pk_mul_f32 v[92:93], v[92:93], v[92:93]
	v_lshl_add_u64 v[106:107], s[20:21], 0, v[106:107]
	v_add_f32_e32 v0, v92, v93
	v_add_f32_e32 v90, v90, v91
	v_lshl_add_u64 v[106:107], v[94:95], 1, v[106:107]
	v_add_f32_e32 v0, v90, v0
	global_store_dwordx2 v[106:107], v[104:105], off
	s_nop 1
	v_mov_b32_dpp v90, v0 quad_perm:[1,0,3,2] row_mask:0xf bank_mask:0xf
	s_waitcnt lgkmcnt(0)
	v_add_f32_e32 v0, v0, v90
	s_nop 1
	v_mov_b32_dpp v90, v0 quad_perm:[2,3,0,1] row_mask:0xf bank_mask:0xf
	s_waitcnt lgkmcnt(0)
	v_add_f32_e32 v0, v0, v90
	s_nop 1
	v_mov_b32_dpp v90, v0 row_half_mirror row_mask:0xf bank_mask:0xf
	s_waitcnt lgkmcnt(0)
	v_add_f32_e32 v90, v0, v90
	s_nop 1
	v_mov_b32_dpp v91, v90 row_ror:8 row_mask:0xf bank_mask:0xf
	s_and_saveexec_b64 s[2:3], s[4:5]
	s_cbranch_execz .LBB0_644
	v_lshlrev_b64 v[92:93], 7, v[96:97]
	v_lshl_add_u64 v[92:93], s[42:43], 0, v[92:93]
	v_lshl_add_u64 v[92:93], s[0:1], 2, v[92:93]
	v_lshlrev_b32_e32 v0, 2, v139
	v_lshl_add_u64 v[92:93], v[92:93], 0, v[0:1]
	s_waitcnt lgkmcnt(0)
	v_add_f32_e32 v0, v90, v91
	global_store_dword v[92:93], v0, off

; DI unsigned pk2(float a, float b) { f32x2 v; v[0] = a; v[1] = b; return __builtin_bit_cast(unsigned, __builtin_convertvector(v, bf16v2)); }
; DI float shx_(float v, int m) { return __int_as_float(__builtin_amdgcn_ds_bpermute((lane_pinned_() ^ m) << 2, __float_as_int(v))); }
; DI int shx_(int v, int m) { return __builtin_amdgcn_ds_bpermute((lane_pinned_() ^ m) << 2, v); }
; DI void gemm_tile(const GD& g, int pm, int pn, bf16_t* shm) {
;     ...
;             if (g.gnext) {
;               u32x2 o2; o2[0] = pk2(x.x * gn.x, x.y * gn.y); o2[1] = pk2(x.z * gn.z, x.w * gn.w);
;               *reinterpret_cast<u32x2*>(g.hbout + (long)grow * DM + gcol) = o2;
;               float sq = (x.x * x.x + x.y * x.y) + (x.z * x.z + x.w * x.w);
;               sq += shx_(sq, 1); sq += shx_(sq, 2); sq += shx_(sq, 4); sq += shx_(sq, 8);
;               if ((lane & 15) == 0) g.ss[(long)grow * 32 + pn * 4 + wc] = sq;
.LBB0_657:
	v_mad_u64_u32 v[104:105], s[2:3], v96, s78, 0
	v_mov_b32_e32 v0, v105
	v_mad_u64_u32 v[106:107], s[2:3], v97, s78, v[0:1]
	v_mov_b32_e32 v105, v106
	v_lshl_add_u64 v[104:105], v[104:105], 2, s[34:35]
	s_waitcnt lgkmcnt(0)
	v_pk_add_f32 v[90:91], v[10:11], v[86:87]
	v_pk_add_f32 v[92:93], v[12:13], v[88:89]
	v_lshl_add_u64 v[104:105], v[94:95], 2, v[104:105]
	s_cmp_eq_u64 s[80:81], 0
	global_store_dwordx4 v[104:105], v[90:93], off
	s_cbranch_scc1 .LBB0_661
	v_pk_mul_f32 v[104:105], v[82:83], v[90:91]
	v_pk_mul_f32 v[106:107], v[84:85], v[92:93]
	v_cvt_pk_bf16_f32 v104, v104, v105
	v_cvt_pk_bf16_f32 v105, v106, v107
	v_lshlrev_b64 v[106:107], 12, v[96:97]
	v_pk_mul_f32 v[90:91], v[90:91], v[90:91]
	v_pk_mul_f32 v[92:93], v[92:93], v[92:93]
	v_lshl_add_u64 v[106:107], s[20:21], 0, v[106:107]
	v_add_f32_e32 v0, v92, v93
	v_add_f32_e32 v90, v90, v91
	v_lshl_add_u64 v[106:107], v[94:95], 1, v[106:107]
	v_add_f32_e32 v0, v90, v0
	global_store_dwordx2 v[106:107], v[104:105], off
	s_nop 1
	v_mov_b32_dpp v90, v0 quad_perm:[1,0,3,2] row_mask:0xf bank_mask:0xf
	s_waitcnt lgkmcnt(0)
	v_add_f32_e32 v0, v0, v90
	s_nop 1
	v_mov_b32_dpp v90, v0 quad_perm:[2,3,0,1] row_mask:0xf bank_mask:0xf
	s_waitcnt lgkmcnt(0)
	v_add_f32_e32 v0, v0, v90
	s_nop 1
	v_mov_b32_dpp v90, v0 row_half_mirror row_mask:0xf bank_mask:0xf
	s_waitcnt lgkmcnt(0)
	v_add_f32_e32 v90, v0, v90
	s_nop 1
	v_mov_b32_dpp v91, v90 row_ror:8 row_mask:0xf bank_mask:0xf
	s_and_saveexec_b64 s[2:3], s[4:5]
	s_cbranch_execz .LBB0_660
	v_lshlrev_b64 v[92:93], 7, v[96:97]
	v_lshl_add_u64 v[92:93], s[42:43], 0, v[92:93]
	v_lshl_add_u64 v[92:93], s[0:1], 2, v[92:93]
	v_lshlrev_b32_e32 v0, 2, v139
	v_lshl_add_u64 v[92:93], v[92:93], 0, v[0:1]
	s_waitcnt lgkmcnt(0)
	v_add_f32_e32 v0, v90, v91
	global_store_dword v[92:93], v0, off

; DI unsigned pk2(float a, float b) { f32x2 v; v[0] = a; v[1] = b; return __builtin_bit_cast(unsigned, __builtin_convertvector(v, bf16v2)); }
; DI float shx_(float v, int m) { return __int_as_float(__builtin_amdgcn_ds_bpermute((lane_pinned_() ^ m) << 2, __float_as_int(v))); }
; DI int shx_(int v, int m) { return __builtin_amdgcn_ds_bpermute((lane_pinned_() ^ m) << 2, v); }
; DI void gemm_tile(const GD& g, int pm, int pn, bf16_t* shm) {
;     ...
;             if (g.gnext) {
;               u32x2 o2; o2[0] = pk2(x.x * gn.x, x.y * gn.y); o2[1] = pk2(x.z * gn.z, x.w * gn.w);
;               *reinterpret_cast<u32x2*>(g.hbout + (long)grow * DM + gcol) = o2;
;               float sq = (x.x * x.x + x.y * x.y) + (x.z * x.z + x.w * x.w);
;               sq += shx_(sq, 1); sq += shx_(sq, 2); sq += shx_(sq, 4); sq += shx_(sq, 8);
;               if ((lane & 15) == 0) g.ss[(long)grow * 32 + pn * 4 + wc] = sq;
.LBB0_673:
	v_mad_u64_u32 v[104:105], s[2:3], v96, s78, 0
	v_mov_b32_e32 v0, v105
	v_mad_u64_u32 v[106:107], s[2:3], v97, s78, v[0:1]
	v_mov_b32_e32 v105, v106
	v_lshl_add_u64 v[104:105], v[104:105], 2, s[34:35]
	s_waitcnt lgkmcnt(0)
	v_pk_add_f32 v[90:91], v[2:3], v[86:87]
	v_pk_add_f32 v[92:93], v[4:5], v[88:89]
	v_lshl_add_u64 v[104:105], v[94:95], 2, v[104:105]
	s_cmp_eq_u64 s[80:81], 0
	global_store_dwordx4 v[104:105], v[90:93], off
	s_cbranch_scc1 .LBB0_677
	v_pk_mul_f32 v[104:105], v[82:83], v[90:91]
	v_pk_mul_f32 v[106:107], v[84:85], v[92:93]
	v_cvt_pk_bf16_f32 v104, v104, v105
	v_cvt_pk_bf16_f32 v105, v106, v107
	v_lshlrev_b64 v[106:107], 12, v[96:97]
	v_pk_mul_f32 v[90:91], v[90:91], v[90:91]
	v_pk_mul_f32 v[92:93], v[92:93], v[92:93]
	v_lshl_add_u64 v[106:107], s[20:21], 0, v[106:107]
	v_add_f32_e32 v0, v92, v93
	v_add_f32_e32 v90, v90, v91
	v_lshl_add_u64 v[106:107], v[94:95], 1, v[106:107]
	v_add_f32_e32 v0, v90, v0
	global_store_dwordx2 v[106:107], v[104:105], off
	s_nop 1
	v_mov_b32_dpp v90, v0 quad_perm:[1,0,3,2] row_mask:0xf bank_mask:0xf
	s_waitcnt lgkmcnt(0)
	v_add_f32_e32 v0, v0, v90
	s_nop 1
	v_mov_b32_dpp v90, v0 quad_perm:[2,3,0,1] row_mask:0xf bank_mask:0xf
	s_waitcnt lgkmcnt(0)
	v_add_f32_e32 v0, v0, v90
	s_nop 1
	v_mov_b32_dpp v90, v0 row_half_mirror row_mask:0xf bank_mask:0xf
	s_waitcnt lgkmcnt(0)
	v_add_f32_e32 v90, v0, v90
	s_nop 1
	v_mov_b32_dpp v91, v90 row_ror:8 row_mask:0xf bank_mask:0xf
	s_and_saveexec_b64 s[2:3], s[4:5]
	s_cbranch_execz .LBB0_676
	v_lshlrev_b64 v[92:93], 7, v[96:97]
	v_lshl_add_u64 v[92:93], s[42:43], 0, v[92:93]
	v_lshl_add_u64 v[92:93], s[0:1], 2, v[92:93]
	v_lshlrev_b32_e32 v0, 2, v139
	v_lshl_add_u64 v[92:93], v[92:93], 0, v[0:1]
	s_waitcnt lgkmcnt(0)
	v_add_f32_e32 v0, v90, v91
	global_store_dword v[92:93], v0, off

; DI unsigned pk2(float a, float b) { f32x2 v; v[0] = a; v[1] = b; return __builtin_bit_cast(unsigned, __builtin_convertvector(v, bf16v2)); }
; DI float shx_(float v, int m) { return __int_as_float(__builtin_amdgcn_ds_bpermute((lane_pinned_() ^ m) << 2, __float_as_int(v))); }
; DI int shx_(int v, int m) { return __builtin_amdgcn_ds_bpermute((lane_pinned_() ^ m) << 2, v); }
; DI void gemm_tile(const GD& g, int pm, int pn, bf16_t* shm) {
;     ...
;             if (g.gnext) {
;               u32x2 o2; o2[0] = pk2(x.x * gn.x, x.y * gn.y); o2[1] = pk2(x.z * gn.z, x.w * gn.w);
;               *reinterpret_cast<u32x2*>(g.hbout + (long)grow * DM + gcol) = o2;
;               float sq = (x.x * x.x + x.y * x.y) + (x.z * x.z + x.w * x.w);
;               sq += shx_(sq, 1); sq += shx_(sq, 2); sq += shx_(sq, 4); sq += shx_(sq, 8);
;               if ((lane & 15) == 0) g.ss[(long)grow * 32 + pn * 4 + wc] = sq;
.LBB0_817:
	v_mad_u64_u32 v[102:103], s[2:3], v96, s78, 0
	v_mov_b32_e32 v0, v103
	v_mad_u64_u32 v[104:105], s[2:3], v97, s78, v[0:1]
	v_mov_b32_e32 v103, v104
	v_lshl_add_u64 v[102:103], v[102:103], 2, s[34:35]
	s_waitcnt vmcnt(0) lgkmcnt(0)
	v_pk_add_f32 v[90:91], v[14:15], v[86:87]
	v_pk_add_f32 v[92:93], v[16:17], v[88:89]
	v_lshl_add_u64 v[102:103], v[94:95], 2, v[102:103]
	s_cmp_eq_u64 s[80:81], 0
	global_store_dwordx4 v[102:103], v[90:93], off
	s_cbranch_scc1 .LBB0_821
	v_pk_mul_f32 v[102:103], v[82:83], v[90:91]
	v_pk_mul_f32 v[104:105], v[84:85], v[92:93]
	v_cvt_pk_bf16_f32 v102, v102, v103
	v_cvt_pk_bf16_f32 v103, v104, v105
	v_lshlrev_b64 v[104:105], 12, v[96:97]
	v_pk_mul_f32 v[90:91], v[90:91], v[90:91]
	v_pk_mul_f32 v[92:93], v[92:93], v[92:93]
	v_lshl_add_u64 v[104:105], s[20:21], 0, v[104:105]
	v_add_f32_e32 v0, v92, v93
	v_add_f32_e32 v90, v90, v91
	v_lshl_add_u64 v[104:105], v[94:95], 1, v[104:105]
	v_add_f32_e32 v0, v90, v0
	global_store_dwordx2 v[104:105], v[102:103], off
	s_nop 1
	v_mov_b32_dpp v90, v0 quad_perm:[1,0,3,2] row_mask:0xf bank_mask:0xf
	s_waitcnt lgkmcnt(0)
	v_add_f32_e32 v0, v0, v90
	s_nop 1
	v_mov_b32_dpp v90, v0 quad_perm:[2,3,0,1] row_mask:0xf bank_mask:0xf
	s_waitcnt lgkmcnt(0)
	v_add_f32_e32 v0, v0, v90
	s_nop 1
	v_mov_b32_dpp v90, v0 row_half_mirror row_mask:0xf bank_mask:0xf
	s_waitcnt lgkmcnt(0)
	v_add_f32_e32 v90, v0, v90
	s_nop 1
	v_mov_b32_dpp v91, v90 row_ror:8 row_mask:0xf bank_mask:0xf
	s_and_saveexec_b64 s[2:3], s[4:5]
	s_cbranch_execz .LBB0_820
	v_lshlrev_b64 v[92:93], 7, v[96:97]
	v_lshl_add_u64 v[92:93], s[42:43], 0, v[92:93]
	v_lshl_add_u64 v[92:93], s[0:1], 2, v[92:93]
	v_lshlrev_b32_e32 v0, 2, v139
	v_lshl_add_u64 v[92:93], v[92:93], 0, v[0:1]
	s_waitcnt lgkmcnt(0)
	v_add_f32_e32 v0, v90, v91
	global_store_dword v[92:93], v0, off

; DI unsigned pk2(float a, float b) { f32x2 v; v[0] = a; v[1] = b; return __builtin_bit_cast(unsigned, __builtin_convertvector(v, bf16v2)); }
; DI float shx_(float v, int m) { return __int_as_float(__builtin_amdgcn_ds_bpermute((lane_pinned_() ^ m) << 2, __float_as_int(v))); }
; DI int shx_(int v, int m) { return __builtin_amdgcn_ds_bpermute((lane_pinned_() ^ m) << 2, v); }
; DI void gemm_tile(const GD& g, int pm, int pn, bf16_t* shm) {
;     ...
;             if (g.gnext) {
;               u32x2 o2; o2[0] = pk2(x.x * gn.x, x.y * gn.y); o2[1] = pk2(x.z * gn.z, x.w * gn.w);
;               *reinterpret_cast<u32x2*>(g.hbout + (long)grow * DM + gcol) = o2;
;               float sq = (x.x * x.x + x.y * x.y) + (x.z * x.z + x.w * x.w);
;               sq += shx_(sq, 1); sq += shx_(sq, 2); sq += shx_(sq, 4); sq += shx_(sq, 8);
;               if ((lane & 15) == 0) g.ss[(long)grow * 32 + pn * 4 + wc] = sq;
.LBB0_839:
	v_mad_u64_u32 v[102:103], s[2:3], v96, s78, 0
	v_mov_b32_e32 v0, v103
	v_mad_u64_u32 v[104:105], s[2:3], v97, s78, v[0:1]
	v_mov_b32_e32 v103, v104
	v_lshl_add_u64 v[102:103], v[102:103], 2, s[34:35]
	s_waitcnt lgkmcnt(0)
	v_pk_add_f32 v[90:91], v[6:7], v[86:87]
	v_pk_add_f32 v[92:93], v[8:9], v[88:89]
	v_lshl_add_u64 v[102:103], v[94:95], 2, v[102:103]
	s_cmp_eq_u64 s[80:81], 0
	global_store_dwordx4 v[102:103], v[90:93], off
	s_cbranch_scc1 .LBB0_843
	v_pk_mul_f32 v[102:103], v[82:83], v[90:91]
	v_pk_mul_f32 v[104:105], v[84:85], v[92:93]
	v_cvt_pk_bf16_f32 v102, v102, v103
	v_cvt_pk_bf16_f32 v103, v104, v105
	v_lshlrev_b64 v[104:105], 12, v[96:97]
	v_pk_mul_f32 v[90:91], v[90:91], v[90:91]
	v_pk_mul_f32 v[92:93], v[92:93], v[92:93]
	v_lshl_add_u64 v[104:105], s[20:21], 0, v[104:105]
	v_add_f32_e32 v0, v92, v93
	v_add_f32_e32 v90, v90, v91
	v_lshl_add_u64 v[104:105], v[94:95], 1, v[104:105]
	v_add_f32_e32 v0, v90, v0
	global_store_dwordx2 v[104:105], v[102:103], off
	s_nop 1
	v_mov_b32_dpp v90, v0 quad_perm:[1,0,3,2] row_mask:0xf bank_mask:0xf
	s_waitcnt lgkmcnt(0)
	v_add_f32_e32 v0, v0, v90
	s_nop 1
	v_mov_b32_dpp v90, v0 quad_perm:[2,3,0,1] row_mask:0xf bank_mask:0xf
	s_waitcnt lgkmcnt(0)
	v_add_f32_e32 v0, v0, v90
	s_nop 1
	v_mov_b32_dpp v90, v0 row_half_mirror row_mask:0xf bank_mask:0xf
	s_waitcnt lgkmcnt(0)
	v_add_f32_e32 v90, v0, v90
	s_nop 1
	v_mov_b32_dpp v91, v90 row_ror:8 row_mask:0xf bank_mask:0xf
	s_and_saveexec_b64 s[2:3], s[4:5]
	s_cbranch_execz .LBB0_842
	v_lshlrev_b64 v[92:93], 7, v[96:97]
	v_lshl_add_u64 v[92:93], s[42:43], 0, v[92:93]
	v_lshl_add_u64 v[92:93], s[0:1], 2, v[92:93]
	v_lshlrev_b32_e32 v0, 2, v139
	v_lshl_add_u64 v[92:93], v[92:93], 0, v[0:1]
	s_waitcnt lgkmcnt(0)
	v_add_f32_e32 v0, v90, v91
	global_store_dword v[92:93], v0, off

; DI unsigned pk2(float a, float b) { f32x2 v; v[0] = a; v[1] = b; return __builtin_bit_cast(unsigned, __builtin_convertvector(v, bf16v2)); }
; DI float shx_(float v, int m) { return __int_as_float(__builtin_amdgcn_ds_bpermute((lane_pinned_() ^ m) << 2, __float_as_int(v))); }
; DI int shx_(int v, int m) { return __builtin_amdgcn_ds_bpermute((lane_pinned_() ^ m) << 2, v); }
; DI void gemm_tile(const GD& g, int pm, int pn, bf16_t* shm) {
;     ...
;             if (g.gnext) {
;               u32x2 o2; o2[0] = pk2(x.x * gn.x, x.y * gn.y); o2[1] = pk2(x.z * gn.z, x.w * gn.w);
;               *reinterpret_cast<u32x2*>(g.hbout + (long)grow * DM + gcol) = o2;
;               float sq = (x.x * x.x + x.y * x.y) + (x.z * x.z + x.w * x.w);
;               sq += shx_(sq, 1); sq += shx_(sq, 2); sq += shx_(sq, 4); sq += shx_(sq, 8);
;               if ((lane & 15) == 0) g.ss[(long)grow * 32 + pn * 4 + wc] = sq;
.LBB0_855:
	v_mad_u64_u32 v[102:103], s[2:3], v96, s78, 0
	v_mov_b32_e32 v0, v103
	v_mad_u64_u32 v[104:105], s[2:3], v97, s78, v[0:1]
	v_mov_b32_e32 v103, v104
	v_lshl_add_u64 v[102:103], v[102:103], 2, s[34:35]
	s_waitcnt lgkmcnt(0)
	v_pk_add_f32 v[90:91], v[10:11], v[86:87]
	v_pk_add_f32 v[92:93], v[12:13], v[88:89]
	v_lshl_add_u64 v[102:103], v[94:95], 2, v[102:103]
	s_cmp_eq_u64 s[80:81], 0
	global_store_dwordx4 v[102:103], v[90:93], off
	s_cbranch_scc1 .LBB0_859
	v_pk_mul_f32 v[102:103], v[82:83], v[90:91]
	v_pk_mul_f32 v[104:105], v[84:85], v[92:93]
	v_cvt_pk_bf16_f32 v102, v102, v103
	v_cvt_pk_bf16_f32 v103, v104, v105
	v_lshlrev_b64 v[104:105], 12, v[96:97]
	v_pk_mul_f32 v[90:91], v[90:91], v[90:91]
	v_pk_mul_f32 v[92:93], v[92:93], v[92:93]
	v_lshl_add_u64 v[104:105], s[20:21], 0, v[104:105]
	v_add_f32_e32 v0, v92, v93
	v_add_f32_e32 v90, v90, v91
	v_lshl_add_u64 v[104:105], v[94:95], 1, v[104:105]
	v_add_f32_e32 v0, v90, v0
	global_store_dwordx2 v[104:105], v[102:103], off
	s_nop 1
	v_mov_b32_dpp v90, v0 quad_perm:[1,0,3,2] row_mask:0xf bank_mask:0xf
	s_waitcnt lgkmcnt(0)
	v_add_f32_e32 v0, v0, v90
	s_nop 1
	v_mov_b32_dpp v90, v0 quad_perm:[2,3,0,1] row_mask:0xf bank_mask:0xf
	s_waitcnt lgkmcnt(0)
	v_add_f32_e32 v0, v0, v90
	s_nop 1
	v_mov_b32_dpp v90, v0 row_half_mirror row_mask:0xf bank_mask:0xf
	s_waitcnt lgkmcnt(0)
	v_add_f32_e32 v90, v0, v90
	s_nop 1
	v_mov_b32_dpp v91, v90 row_ror:8 row_mask:0xf bank_mask:0xf
	s_and_saveexec_b64 s[2:3], s[4:5]
	s_cbranch_execz .LBB0_858
	v_lshlrev_b64 v[92:93], 7, v[96:97]
	v_lshl_add_u64 v[92:93], s[42:43], 0, v[92:93]
	v_lshl_add_u64 v[92:93], s[0:1], 2, v[92:93]
	v_lshlrev_b32_e32 v0, 2, v139
	v_lshl_add_u64 v[92:93], v[92:93], 0, v[0:1]
	s_waitcnt lgkmcnt(0)
	v_add_f32_e32 v0, v90, v91
	global_store_dword v[92:93], v0, off

; DI unsigned pk2(float a, float b) { f32x2 v; v[0] = a; v[1] = b; return __builtin_bit_cast(unsigned, __builtin_convertvector(v, bf16v2)); }
; DI float shx_(float v, int m) { return __int_as_float(__builtin_amdgcn_ds_bpermute((lane_pinned_() ^ m) << 2, __float_as_int(v))); }
; DI int shx_(int v, int m) { return __builtin_amdgcn_ds_bpermute((lane_pinned_() ^ m) << 2, v); }
; DI void gemm_tile(const GD& g, int pm, int pn, bf16_t* shm) {
;     ...
;             if (g.gnext) {
;               u32x2 o2; o2[0] = pk2(x.x * gn.x, x.y * gn.y); o2[1] = pk2(x.z * gn.z, x.w * gn.w);
;               *reinterpret_cast<u32x2*>(g.hbout + (long)grow * DM + gcol) = o2;
;               float sq = (x.x * x.x + x.y * x.y) + (x.z * x.z + x.w * x.w);
;               sq += shx_(sq, 1); sq += shx_(sq, 2); sq += shx_(sq, 4); sq += shx_(sq, 8);
;               if ((lane & 15) == 0) g.ss[(long)grow * 32 + pn * 4 + wc] = sq;
.LBB0_871:
	v_mad_u64_u32 v[102:103], s[2:3], v96, s78, 0
	v_mov_b32_e32 v0, v103
	v_mad_u64_u32 v[104:105], s[2:3], v97, s78, v[0:1]
	v_mov_b32_e32 v103, v104
	v_lshl_add_u64 v[102:103], v[102:103], 2, s[34:35]
	s_waitcnt lgkmcnt(0)
	v_pk_add_f32 v[90:91], v[2:3], v[86:87]
	v_pk_add_f32 v[92:93], v[4:5], v[88:89]
	v_lshl_add_u64 v[102:103], v[94:95], 2, v[102:103]
	s_cmp_eq_u64 s[80:81], 0
	global_store_dwordx4 v[102:103], v[90:93], off
	s_cbranch_scc1 .LBB0_875
	v_pk_mul_f32 v[82:83], v[82:83], v[90:91]
	v_pk_mul_f32 v[84:85], v[84:85], v[92:93]
	v_cvt_pk_bf16_f32 v82, v82, v83
	v_cvt_pk_bf16_f32 v83, v84, v85
	v_lshlrev_b64 v[84:85], 12, v[96:97]
	v_lshl_add_u64 v[84:85], s[20:21], 0, v[84:85]
	v_lshl_add_u64 v[84:85], v[94:95], 1, v[84:85]
	global_store_dwordx2 v[84:85], v[82:83], off
	v_pk_mul_f32 v[82:83], v[90:91], v[90:91]
	v_pk_mul_f32 v[84:85], v[92:93], v[92:93]
	v_add_f32_e32 v82, v82, v83
	v_add_f32_e32 v0, v84, v85
	v_add_f32_e32 v0, v82, v0
	s_nop 1
	v_mov_b32_dpp v82, v0 quad_perm:[1,0,3,2] row_mask:0xf bank_mask:0xf
	s_waitcnt lgkmcnt(0)
	v_add_f32_e32 v0, v0, v82
	s_nop 1
	v_mov_b32_dpp v82, v0 quad_perm:[2,3,0,1] row_mask:0xf bank_mask:0xf
	s_waitcnt lgkmcnt(0)
	v_add_f32_e32 v0, v0, v82
	s_nop 1
	v_mov_b32_dpp v82, v0 row_half_mirror row_mask:0xf bank_mask:0xf
	s_waitcnt lgkmcnt(0)
	v_add_f32_e32 v82, v0, v82
	s_nop 1
	v_mov_b32_dpp v83, v82 row_ror:8 row_mask:0xf bank_mask:0xf
	s_and_saveexec_b64 s[2:3], s[4:5]
	s_cbranch_execz .LBB0_874
	v_lshlrev_b64 v[84:85], 7, v[96:97]
	v_lshl_add_u64 v[84:85], s[42:43], 0, v[84:85]
	v_lshl_add_u64 v[84:85], s[0:1], 2, v[84:85]
	v_lshlrev_b32_e32 v0, 2, v139
	v_lshl_add_u64 v[84:85], v[84:85], 0, v[0:1]
	s_waitcnt lgkmcnt(0)
	v_add_f32_e32 v0, v82, v83
	global_store_dword v[84:85], v0, off

; DI unsigned pk2(float a, float b) { f32x2 v; v[0] = a; v[1] = b; return __builtin_bit_cast(unsigned, __builtin_convertvector(v, bf16v2)); }
; DI float shx_(float v, int m) { return __int_as_float(__builtin_amdgcn_ds_bpermute((lane_pinned_() ^ m) << 2, __float_as_int(v))); }
; DI int shx_(int v, int m) { return __builtin_amdgcn_ds_bpermute((lane_pinned_() ^ m) << 2, v); }
; DI void gemm_tile(const GD& g, int pm, int pn, bf16_t* shm) {
;     ...
;             if (g.gnext) {
;               u32x2 o2; o2[0] = pk2(x.x * gn.x, x.y * gn.y); o2[1] = pk2(x.z * gn.z, x.w * gn.w);
;               *reinterpret_cast<u32x2*>(g.hbout + (long)grow * DM + gcol) = o2;
;               float sq = (x.x * x.x + x.y * x.y) + (x.z * x.z + x.w * x.w);
;               sq += shx_(sq, 1); sq += shx_(sq, 2); sq += shx_(sq, 4); sq += shx_(sq, 8);
;               if ((lane & 15) == 0) g.ss[(long)grow * 32 + pn * 4 + wc] = sq;
.LBB0_1035:
	v_mad_u64_u32 v[36:37], s[2:3], v32, s78, 0
	v_mov_b32_e32 v0, v37
	v_mad_u64_u32 v[38:39], s[2:3], v33, s78, v[0:1]
	v_mov_b32_e32 v37, v38
	v_lshl_add_u64 v[36:37], v[36:37], 2, s[34:35]
	s_waitcnt vmcnt(0) lgkmcnt(0)
	v_pk_add_f32 v[26:27], v[14:15], v[22:23]
	v_pk_add_f32 v[28:29], v[16:17], v[24:25]
	v_lshl_add_u64 v[36:37], v[94:95], 2, v[36:37]
	s_cmp_eq_u64 s[80:81], 0
	global_store_dwordx4 v[36:37], v[26:29], off
	s_cbranch_scc1 .LBB0_1039
	v_pk_mul_f32 v[36:37], v[18:19], v[26:27]
	v_pk_mul_f32 v[38:39], v[20:21], v[28:29]
	v_cvt_pk_bf16_f32 v36, v36, v37
	v_cvt_pk_bf16_f32 v37, v38, v39
	v_lshlrev_b64 v[38:39], 12, v[32:33]
	v_pk_mul_f32 v[26:27], v[26:27], v[26:27]
	v_pk_mul_f32 v[28:29], v[28:29], v[28:29]
	v_lshl_add_u64 v[38:39], s[20:21], 0, v[38:39]
	v_add_f32_e32 v0, v28, v29
	v_add_f32_e32 v26, v26, v27
	v_lshl_add_u64 v[38:39], v[94:95], 1, v[38:39]
	v_add_f32_e32 v0, v26, v0
	global_store_dwordx2 v[38:39], v[36:37], off
	s_nop 1
	v_mov_b32_dpp v26, v0 quad_perm:[1,0,3,2] row_mask:0xf bank_mask:0xf
	s_waitcnt lgkmcnt(0)
	v_add_f32_e32 v0, v0, v26
	s_nop 1
	v_mov_b32_dpp v26, v0 quad_perm:[2,3,0,1] row_mask:0xf bank_mask:0xf
	s_waitcnt lgkmcnt(0)
	v_add_f32_e32 v0, v0, v26
	s_nop 1
	v_mov_b32_dpp v26, v0 row_half_mirror row_mask:0xf bank_mask:0xf
	s_waitcnt lgkmcnt(0)
	v_add_f32_e32 v26, v0, v26
	s_nop 1
	v_mov_b32_dpp v27, v26 row_ror:8 row_mask:0xf bank_mask:0xf
	s_and_saveexec_b64 s[2:3], s[4:5]
	s_cbranch_execz .LBB0_1038
	v_lshlrev_b64 v[28:29], 7, v[32:33]
	v_lshl_add_u64 v[28:29], s[42:43], 0, v[28:29]
	v_lshl_add_u64 v[28:29], s[0:1], 2, v[28:29]
	v_lshlrev_b32_e32 v0, 2, v139
	v_lshl_add_u64 v[28:29], v[28:29], 0, v[0:1]
	s_waitcnt lgkmcnt(0)
	v_add_f32_e32 v0, v26, v27
	global_store_dword v[28:29], v0, off

; DI unsigned pk2(float a, float b) { f32x2 v; v[0] = a; v[1] = b; return __builtin_bit_cast(unsigned, __builtin_convertvector(v, bf16v2)); }
; DI float shx_(float v, int m) { return __int_as_float(__builtin_amdgcn_ds_bpermute((lane_pinned_() ^ m) << 2, __float_as_int(v))); }
; DI int shx_(int v, int m) { return __builtin_amdgcn_ds_bpermute((lane_pinned_() ^ m) << 2, v); }
; DI void gemm_tile(const GD& g, int pm, int pn, bf16_t* shm) {
;     ...
;             if (g.gnext) {
;               u32x2 o2; o2[0] = pk2(x.x * gn.x, x.y * gn.y); o2[1] = pk2(x.z * gn.z, x.w * gn.w);
;               *reinterpret_cast<u32x2*>(g.hbout + (long)grow * DM + gcol) = o2;
;               float sq = (x.x * x.x + x.y * x.y) + (x.z * x.z + x.w * x.w);
;               sq += shx_(sq, 1); sq += shx_(sq, 2); sq += shx_(sq, 4); sq += shx_(sq, 8);
;               if ((lane & 15) == 0) g.ss[(long)grow * 32 + pn * 4 + wc] = sq;
.LBB0_1051:
	v_mad_u64_u32 v[36:37], s[2:3], v32, s78, 0
	v_mov_b32_e32 v0, v37
	v_mad_u64_u32 v[38:39], s[2:3], v33, s78, v[0:1]
	v_mov_b32_e32 v37, v38
	v_lshl_add_u64 v[36:37], v[36:37], 2, s[34:35]
	s_waitcnt lgkmcnt(0)
	v_pk_add_f32 v[26:27], v[6:7], v[22:23]
	v_pk_add_f32 v[28:29], v[8:9], v[24:25]
	v_lshl_add_u64 v[36:37], v[94:95], 2, v[36:37]
	s_cmp_eq_u64 s[80:81], 0
	global_store_dwordx4 v[36:37], v[26:29], off
	s_cbranch_scc1 .LBB0_1055
	v_pk_mul_f32 v[36:37], v[18:19], v[26:27]
	v_pk_mul_f32 v[38:39], v[20:21], v[28:29]
	v_cvt_pk_bf16_f32 v36, v36, v37
	v_cvt_pk_bf16_f32 v37, v38, v39
	v_lshlrev_b64 v[38:39], 12, v[32:33]
	v_pk_mul_f32 v[26:27], v[26:27], v[26:27]
	v_pk_mul_f32 v[28:29], v[28:29], v[28:29]
	v_lshl_add_u64 v[38:39], s[20:21], 0, v[38:39]
	v_add_f32_e32 v0, v28, v29
	v_add_f32_e32 v26, v26, v27
	v_lshl_add_u64 v[38:39], v[94:95], 1, v[38:39]
	v_add_f32_e32 v0, v26, v0
	global_store_dwordx2 v[38:39], v[36:37], off
	s_nop 1
	v_mov_b32_dpp v26, v0 quad_perm:[1,0,3,2] row_mask:0xf bank_mask:0xf
	s_waitcnt lgkmcnt(0)
	v_add_f32_e32 v0, v0, v26
	s_nop 1
	v_mov_b32_dpp v26, v0 quad_perm:[2,3,0,1] row_mask:0xf bank_mask:0xf
	s_waitcnt lgkmcnt(0)
	v_add_f32_e32 v0, v0, v26
	s_nop 1
	v_mov_b32_dpp v26, v0 row_half_mirror row_mask:0xf bank_mask:0xf
	s_waitcnt lgkmcnt(0)
	v_add_f32_e32 v26, v0, v26
	s_nop 1
	v_mov_b32_dpp v27, v26 row_ror:8 row_mask:0xf bank_mask:0xf
	s_and_saveexec_b64 s[2:3], s[4:5]
	s_cbranch_execz .LBB0_1054
	v_lshlrev_b64 v[28:29], 7, v[32:33]
	v_lshl_add_u64 v[28:29], s[42:43], 0, v[28:29]
	v_lshl_add_u64 v[28:29], s[0:1], 2, v[28:29]
	v_lshlrev_b32_e32 v0, 2, v139
	v_lshl_add_u64 v[28:29], v[28:29], 0, v[0:1]
	s_waitcnt lgkmcnt(0)
	v_add_f32_e32 v0, v26, v27
	global_store_dword v[28:29], v0, off

; DI unsigned pk2(float a, float b) { f32x2 v; v[0] = a; v[1] = b; return __builtin_bit_cast(unsigned, __builtin_convertvector(v, bf16v2)); }
; DI float shx_(float v, int m) { return __int_as_float(__builtin_amdgcn_ds_bpermute((lane_pinned_() ^ m) << 2, __float_as_int(v))); }
; DI int shx_(int v, int m) { return __builtin_amdgcn_ds_bpermute((lane_pinned_() ^ m) << 2, v); }
; DI void gemm_tile(const GD& g, int pm, int pn, bf16_t* shm) {
;     ...
;             if (g.gnext) {
;               u32x2 o2; o2[0] = pk2(x.x * gn.x, x.y * gn.y); o2[1] = pk2(x.z * gn.z, x.w * gn.w);
;               *reinterpret_cast<u32x2*>(g.hbout + (long)grow * DM + gcol) = o2;
;               float sq = (x.x * x.x + x.y * x.y) + (x.z * x.z + x.w * x.w);
;               sq += shx_(sq, 1); sq += shx_(sq, 2); sq += shx_(sq, 4); sq += shx_(sq, 8);
;               if ((lane & 15) == 0) g.ss[(long)grow * 32 + pn * 4 + wc] = sq;
.LBB0_1067:
	v_mad_u64_u32 v[36:37], s[2:3], v32, s78, 0
	v_mov_b32_e32 v0, v37
	v_mad_u64_u32 v[38:39], s[2:3], v33, s78, v[0:1]
	v_mov_b32_e32 v37, v38
	v_lshl_add_u64 v[36:37], v[36:37], 2, s[34:35]
	s_waitcnt lgkmcnt(0)
	v_pk_add_f32 v[26:27], v[10:11], v[22:23]
	v_pk_add_f32 v[28:29], v[12:13], v[24:25]
	v_lshl_add_u64 v[36:37], v[94:95], 2, v[36:37]
	s_cmp_eq_u64 s[80:81], 0
	global_store_dwordx4 v[36:37], v[26:29], off
	s_cbranch_scc1 .LBB0_1071
	v_pk_mul_f32 v[36:37], v[18:19], v[26:27]
	v_pk_mul_f32 v[38:39], v[20:21], v[28:29]
	v_cvt_pk_bf16_f32 v36, v36, v37
	v_cvt_pk_bf16_f32 v37, v38, v39
	v_lshlrev_b64 v[38:39], 12, v[32:33]
	v_pk_mul_f32 v[26:27], v[26:27], v[26:27]
	v_pk_mul_f32 v[28:29], v[28:29], v[28:29]
	v_lshl_add_u64 v[38:39], s[20:21], 0, v[38:39]
	v_add_f32_e32 v0, v28, v29
	v_add_f32_e32 v26, v26, v27
	v_lshl_add_u64 v[38:39], v[94:95], 1, v[38:39]
	v_add_f32_e32 v0, v26, v0
	global_store_dwordx2 v[38:39], v[36:37], off
	s_nop 1
	v_mov_b32_dpp v26, v0 quad_perm:[1,0,3,2] row_mask:0xf bank_mask:0xf
	s_waitcnt lgkmcnt(0)
	v_add_f32_e32 v0, v0, v26
	s_nop 1
	v_mov_b32_dpp v26, v0 quad_perm:[2,3,0,1] row_mask:0xf bank_mask:0xf
	s_waitcnt lgkmcnt(0)
	v_add_f32_e32 v0, v0, v26
	s_nop 1
	v_mov_b32_dpp v26, v0 row_half_mirror row_mask:0xf bank_mask:0xf
	s_waitcnt lgkmcnt(0)
	v_add_f32_e32 v26, v0, v26
	s_nop 1
	v_mov_b32_dpp v27, v26 row_ror:8 row_mask:0xf bank_mask:0xf
	s_and_saveexec_b64 s[2:3], s[4:5]
	s_cbranch_execz .LBB0_1070
	v_lshlrev_b64 v[28:29], 7, v[32:33]
	v_lshl_add_u64 v[28:29], s[42:43], 0, v[28:29]
	v_lshl_add_u64 v[28:29], s[0:1], 2, v[28:29]
	v_lshlrev_b32_e32 v0, 2, v139
	v_lshl_add_u64 v[28:29], v[28:29], 0, v[0:1]
	s_waitcnt lgkmcnt(0)
	v_add_f32_e32 v0, v26, v27
	global_store_dword v[28:29], v0, off

; DI unsigned pk2(float a, float b) { f32x2 v; v[0] = a; v[1] = b; return __builtin_bit_cast(unsigned, __builtin_convertvector(v, bf16v2)); }
; DI float shx_(float v, int m) { return __int_as_float(__builtin_amdgcn_ds_bpermute((lane_pinned_() ^ m) << 2, __float_as_int(v))); }
; DI int shx_(int v, int m) { return __builtin_amdgcn_ds_bpermute((lane_pinned_() ^ m) << 2, v); }
; DI void gemm_tile(const GD& g, int pm, int pn, bf16_t* shm) {
;     ...
;             if (g.gnext) {
;               u32x2 o2; o2[0] = pk2(x.x * gn.x, x.y * gn.y); o2[1] = pk2(x.z * gn.z, x.w * gn.w);
;               *reinterpret_cast<u32x2*>(g.hbout + (long)grow * DM + gcol) = o2;
;               float sq = (x.x * x.x + x.y * x.y) + (x.z * x.z + x.w * x.w);
;               sq += shx_(sq, 1); sq += shx_(sq, 2); sq += shx_(sq, 4); sq += shx_(sq, 8);
;               if ((lane & 15) == 0) g.ss[(long)grow * 32 + pn * 4 + wc] = sq;
.LBB0_1083:
	v_mad_u64_u32 v[36:37], s[2:3], v32, s78, 0
	v_mov_b32_e32 v0, v37
	v_mad_u64_u32 v[38:39], s[2:3], v33, s78, v[0:1]
	v_mov_b32_e32 v37, v38
	v_lshl_add_u64 v[36:37], v[36:37], 2, s[34:35]
	s_waitcnt lgkmcnt(0)
	v_pk_add_f32 v[26:27], v[2:3], v[22:23]
	v_pk_add_f32 v[28:29], v[4:5], v[24:25]
	v_lshl_add_u64 v[36:37], v[94:95], 2, v[36:37]
	s_cmp_eq_u64 s[80:81], 0
	global_store_dwordx4 v[36:37], v[26:29], off
	s_cbranch_scc1 .LBB0_1087
	v_pk_mul_f32 v[36:37], v[18:19], v[26:27]
	v_pk_mul_f32 v[38:39], v[20:21], v[28:29]
	v_cvt_pk_bf16_f32 v36, v36, v37
	v_cvt_pk_bf16_f32 v37, v38, v39
	v_lshlrev_b64 v[38:39], 12, v[32:33]
	v_pk_mul_f32 v[26:27], v[26:27], v[26:27]
	v_pk_mul_f32 v[28:29], v[28:29], v[28:29]
	v_lshl_add_u64 v[38:39], s[20:21], 0, v[38:39]
	v_add_f32_e32 v0, v28, v29
	v_add_f32_e32 v26, v26, v27
	v_lshl_add_u64 v[38:39], v[94:95], 1, v[38:39]
	v_add_f32_e32 v0, v26, v0
	global_store_dwordx2 v[38:39], v[36:37], off
	s_nop 1
	v_mov_b32_dpp v26, v0 quad_perm:[1,0,3,2] row_mask:0xf bank_mask:0xf
	s_waitcnt lgkmcnt(0)
	v_add_f32_e32 v0, v0, v26
	s_nop 1
	v_mov_b32_dpp v26, v0 quad_perm:[2,3,0,1] row_mask:0xf bank_mask:0xf
	s_waitcnt lgkmcnt(0)
	v_add_f32_e32 v0, v0, v26
	s_nop 1
	v_mov_b32_dpp v26, v0 row_half_mirror row_mask:0xf bank_mask:0xf
	s_waitcnt lgkmcnt(0)
	v_add_f32_e32 v26, v0, v26
	s_nop 1
	v_mov_b32_dpp v27, v26 row_ror:8 row_mask:0xf bank_mask:0xf
	s_and_saveexec_b64 s[2:3], s[4:5]
	s_cbranch_execz .LBB0_1086
	v_lshlrev_b64 v[28:29], 7, v[32:33]
	v_lshl_add_u64 v[28:29], s[42:43], 0, v[28:29]
	v_lshl_add_u64 v[28:29], s[0:1], 2, v[28:29]
	v_lshlrev_b32_e32 v0, 2, v139
	v_lshl_add_u64 v[28:29], v[28:29], 0, v[0:1]
	s_waitcnt lgkmcnt(0)
	v_add_f32_e32 v0, v26, v27
	global_store_dword v[28:29], v0, off

; DI unsigned pk2(float a, float b) { f32x2 v; v[0] = a; v[1] = b; return __builtin_bit_cast(unsigned, __builtin_convertvector(v, bf16v2)); }
; DI float shx_(float v, int m) { return __int_as_float(__builtin_amdgcn_ds_bpermute((lane_pinned_() ^ m) << 2, __float_as_int(v))); }
; DI int shx_(int v, int m) { return __builtin_amdgcn_ds_bpermute((lane_pinned_() ^ m) << 2, v); }
; DI void gemm_tile(const GD& g, int pm, int pn, bf16_t* shm) {
;     ...
;             if (g.gnext) {
;               u32x2 o2; o2[0] = pk2(x.x * gn.x, x.y * gn.y); o2[1] = pk2(x.z * gn.z, x.w * gn.w);
;               *reinterpret_cast<u32x2*>(g.hbout + (long)grow * DM + gcol) = o2;
;               float sq = (x.x * x.x + x.y * x.y) + (x.z * x.z + x.w * x.w);
;               sq += shx_(sq, 1); sq += shx_(sq, 2); sq += shx_(sq, 4); sq += shx_(sq, 8);
;               if ((lane & 15) == 0) g.ss[(long)grow * 32 + pn * 4 + wc] = sq;
.LBB0_1227:
	v_mad_u64_u32 v[28:29], s[2:3], v26, s78, 0
	v_mov_b32_e32 v0, v29
	v_mad_u64_u32 v[30:31], s[2:3], v27, s78, v[0:1]
	v_mov_b32_e32 v29, v30
	v_lshl_add_u64 v[28:29], v[28:29], 2, s[34:35]
	s_waitcnt vmcnt(0) lgkmcnt(0)
	v_pk_add_f32 v[14:15], v[14:15], v[22:23]
	v_pk_add_f32 v[16:17], v[16:17], v[24:25]
	v_lshl_add_u64 v[28:29], v[94:95], 2, v[28:29]
	s_cmp_eq_u64 s[80:81], 0
	global_store_dwordx4 v[28:29], v[14:17], off
	s_cbranch_scc1 .LBB0_1231
	v_pk_mul_f32 v[28:29], v[18:19], v[14:15]
	v_pk_mul_f32 v[30:31], v[20:21], v[16:17]
	v_cvt_pk_bf16_f32 v28, v28, v29
	v_cvt_pk_bf16_f32 v29, v30, v31
	v_lshlrev_b64 v[30:31], 12, v[26:27]
	v_pk_mul_f32 v[14:15], v[14:15], v[14:15]
	v_pk_mul_f32 v[16:17], v[16:17], v[16:17]
	v_lshl_add_u64 v[30:31], s[20:21], 0, v[30:31]
	v_add_f32_e32 v0, v16, v17
	v_add_f32_e32 v14, v14, v15
	v_lshl_add_u64 v[30:31], v[94:95], 1, v[30:31]
	v_add_f32_e32 v0, v14, v0
	global_store_dwordx2 v[30:31], v[28:29], off
	s_nop 1
	v_mov_b32_dpp v14, v0 quad_perm:[1,0,3,2] row_mask:0xf bank_mask:0xf
	s_waitcnt lgkmcnt(0)
	v_add_f32_e32 v0, v0, v14
	s_nop 1
	v_mov_b32_dpp v14, v0 quad_perm:[2,3,0,1] row_mask:0xf bank_mask:0xf
	s_waitcnt lgkmcnt(0)
	v_add_f32_e32 v0, v0, v14
	s_nop 1
	v_mov_b32_dpp v14, v0 row_half_mirror row_mask:0xf bank_mask:0xf
	s_waitcnt lgkmcnt(0)
	v_add_f32_e32 v14, v0, v14
	s_nop 1
	v_mov_b32_dpp v15, v14 row_ror:8 row_mask:0xf bank_mask:0xf
	s_and_saveexec_b64 s[2:3], s[4:5]
	s_cbranch_execz .LBB0_1230
	v_lshlrev_b64 v[16:17], 7, v[26:27]
	v_lshl_add_u64 v[16:17], s[42:43], 0, v[16:17]
	v_lshl_add_u64 v[16:17], s[0:1], 2, v[16:17]
	v_lshlrev_b32_e32 v0, 2, v139
	v_lshl_add_u64 v[16:17], v[16:17], 0, v[0:1]
	s_waitcnt lgkmcnt(0)
	v_add_f32_e32 v0, v14, v15
	global_store_dword v[16:17], v0, off

; DI unsigned pk2(float a, float b) { f32x2 v; v[0] = a; v[1] = b; return __builtin_bit_cast(unsigned, __builtin_convertvector(v, bf16v2)); }
; DI float shx_(float v, int m) { return __int_as_float(__builtin_amdgcn_ds_bpermute((lane_pinned_() ^ m) << 2, __float_as_int(v))); }
; DI int shx_(int v, int m) { return __builtin_amdgcn_ds_bpermute((lane_pinned_() ^ m) << 2, v); }
; DI void gemm_tile(const GD& g, int pm, int pn, bf16_t* shm) {
;     ...
;             if (g.gnext) {
;               u32x2 o2; o2[0] = pk2(x.x * gn.x, x.y * gn.y); o2[1] = pk2(x.z * gn.z, x.w * gn.w);
;               *reinterpret_cast<u32x2*>(g.hbout + (long)grow * DM + gcol) = o2;
;               float sq = (x.x * x.x + x.y * x.y) + (x.z * x.z + x.w * x.w);
;               sq += shx_(sq, 1); sq += shx_(sq, 2); sq += shx_(sq, 4); sq += shx_(sq, 8);
;               if ((lane & 15) == 0) g.ss[(long)grow * 32 + pn * 4 + wc] = sq;
.LBB0_1249:
	v_mad_u64_u32 v[24:25], s[2:3], v22, s78, 0
	v_mov_b32_e32 v0, v25
	v_mad_u64_u32 v[26:27], s[2:3], v23, s78, v[0:1]
	v_mov_b32_e32 v25, v26
	v_lshl_add_u64 v[24:25], v[24:25], 2, s[34:35]
	s_waitcnt lgkmcnt(0)
	v_pk_add_f32 v[6:7], v[6:7], v[14:15]
	v_pk_add_f32 v[8:9], v[8:9], v[16:17]
	v_lshl_add_u64 v[24:25], v[94:95], 2, v[24:25]
	s_cmp_eq_u64 s[80:81], 0
	global_store_dwordx4 v[24:25], v[6:9], off
	s_cbranch_scc1 .LBB0_1253
	v_pk_mul_f32 v[24:25], v[18:19], v[6:7]
	v_pk_mul_f32 v[26:27], v[20:21], v[8:9]
	v_cvt_pk_bf16_f32 v24, v24, v25
	v_cvt_pk_bf16_f32 v25, v26, v27
	v_lshlrev_b64 v[26:27], 12, v[22:23]
	v_pk_mul_f32 v[6:7], v[6:7], v[6:7]
	v_pk_mul_f32 v[8:9], v[8:9], v[8:9]
	v_lshl_add_u64 v[26:27], s[20:21], 0, v[26:27]
	v_add_f32_e32 v0, v8, v9
	v_add_f32_e32 v6, v6, v7
	v_lshl_add_u64 v[26:27], v[94:95], 1, v[26:27]
	v_add_f32_e32 v0, v6, v0
	global_store_dwordx2 v[26:27], v[24:25], off
	s_nop 1
	v_mov_b32_dpp v6, v0 quad_perm:[1,0,3,2] row_mask:0xf bank_mask:0xf
	s_waitcnt lgkmcnt(0)
	v_add_f32_e32 v0, v0, v6
	s_nop 1
	v_mov_b32_dpp v6, v0 quad_perm:[2,3,0,1] row_mask:0xf bank_mask:0xf
	s_waitcnt lgkmcnt(0)
	v_add_f32_e32 v0, v0, v6
	s_nop 1
	v_mov_b32_dpp v6, v0 row_half_mirror row_mask:0xf bank_mask:0xf
	s_waitcnt lgkmcnt(0)
	v_add_f32_e32 v6, v0, v6
	s_nop 1
	v_mov_b32_dpp v7, v6 row_ror:8 row_mask:0xf bank_mask:0xf
	s_and_saveexec_b64 s[2:3], s[4:5]
	s_cbranch_execz .LBB0_1252
	v_lshlrev_b64 v[8:9], 7, v[22:23]
	v_lshl_add_u64 v[8:9], s[42:43], 0, v[8:9]
	v_lshl_add_u64 v[8:9], s[0:1], 2, v[8:9]
	v_lshlrev_b32_e32 v0, 2, v139
	v_lshl_add_u64 v[8:9], v[8:9], 0, v[0:1]
	s_waitcnt lgkmcnt(0)
	v_add_f32_e32 v0, v6, v7
	global_store_dword v[8:9], v0, off

; DI unsigned pk2(float a, float b) { f32x2 v; v[0] = a; v[1] = b; return __builtin_bit_cast(unsigned, __builtin_convertvector(v, bf16v2)); }
; DI float shx_(float v, int m) { return __int_as_float(__builtin_amdgcn_ds_bpermute((lane_pinned_() ^ m) << 2, __float_as_int(v))); }
; DI int shx_(int v, int m) { return __builtin_amdgcn_ds_bpermute((lane_pinned_() ^ m) << 2, v); }
; DI void gemm_tile(const GD& g, int pm, int pn, bf16_t* shm) {
;     ...
;             if (g.gnext) {
;               u32x2 o2; o2[0] = pk2(x.x * gn.x, x.y * gn.y); o2[1] = pk2(x.z * gn.z, x.w * gn.w);
;               *reinterpret_cast<u32x2*>(g.hbout + (long)grow * DM + gcol) = o2;
;               float sq = (x.x * x.x + x.y * x.y) + (x.z * x.z + x.w * x.w);
;               sq += shx_(sq, 1); sq += shx_(sq, 2); sq += shx_(sq, 4); sq += shx_(sq, 8);
;               if ((lane & 15) == 0) g.ss[(long)grow * 32 + pn * 4 + wc] = sq;
.LBB0_1265:
	v_mad_u64_u32 v[16:17], s[2:3], v14, s78, 0
	v_mov_b32_e32 v0, v17
	v_mad_u64_u32 v[22:23], s[2:3], v15, s78, v[0:1]
	v_mov_b32_e32 v17, v22
	v_lshl_add_u64 v[16:17], v[16:17], 2, s[34:35]
	s_waitcnt lgkmcnt(0)
	v_pk_add_f32 v[10:11], v[10:11], v[6:7]
	v_pk_add_f32 v[12:13], v[12:13], v[8:9]
	v_lshl_add_u64 v[16:17], v[94:95], 2, v[16:17]
	s_cmp_eq_u64 s[80:81], 0
	global_store_dwordx4 v[16:17], v[10:13], off
	s_cbranch_scc1 .LBB0_1269
	v_pk_mul_f32 v[16:17], v[18:19], v[10:11]
	v_pk_mul_f32 v[22:23], v[20:21], v[12:13]
	v_cvt_pk_bf16_f32 v16, v16, v17
	v_cvt_pk_bf16_f32 v17, v22, v23
	v_lshlrev_b64 v[22:23], 12, v[14:15]
	v_pk_mul_f32 v[10:11], v[10:11], v[10:11]
	v_pk_mul_f32 v[12:13], v[12:13], v[12:13]
	v_lshl_add_u64 v[22:23], s[20:21], 0, v[22:23]
	v_add_f32_e32 v0, v12, v13
	v_add_f32_e32 v10, v10, v11
	v_lshl_add_u64 v[22:23], v[94:95], 1, v[22:23]
	v_add_f32_e32 v0, v10, v0
	global_store_dwordx2 v[22:23], v[16:17], off
	s_nop 1
	v_mov_b32_dpp v10, v0 quad_perm:[1,0,3,2] row_mask:0xf bank_mask:0xf
	s_waitcnt lgkmcnt(0)
	v_add_f32_e32 v0, v0, v10
	s_nop 1
	v_mov_b32_dpp v10, v0 quad_perm:[2,3,0,1] row_mask:0xf bank_mask:0xf
	s_waitcnt lgkmcnt(0)
	v_add_f32_e32 v0, v0, v10
	s_nop 1
	v_mov_b32_dpp v10, v0 row_half_mirror row_mask:0xf bank_mask:0xf
	s_waitcnt lgkmcnt(0)
	v_add_f32_e32 v10, v0, v10
	s_nop 1
	v_mov_b32_dpp v11, v10 row_ror:8 row_mask:0xf bank_mask:0xf
	s_and_saveexec_b64 s[2:3], s[4:5]
	s_cbranch_execz .LBB0_1268
	v_lshlrev_b64 v[12:13], 7, v[14:15]
	v_lshl_add_u64 v[12:13], s[42:43], 0, v[12:13]
	v_lshl_add_u64 v[12:13], s[0:1], 2, v[12:13]
	v_lshlrev_b32_e32 v0, 2, v139
	v_lshl_add_u64 v[12:13], v[12:13], 0, v[0:1]
	s_waitcnt lgkmcnt(0)
	v_add_f32_e32 v0, v10, v11
	global_store_dword v[12:13], v0, off

; DI unsigned pk2(float a, float b) { f32x2 v; v[0] = a; v[1] = b; return __builtin_bit_cast(unsigned, __builtin_convertvector(v, bf16v2)); }
; DI float shx_(float v, int m) { return __int_as_float(__builtin_amdgcn_ds_bpermute((lane_pinned_() ^ m) << 2, __float_as_int(v))); }
; DI int shx_(int v, int m) { return __builtin_amdgcn_ds_bpermute((lane_pinned_() ^ m) << 2, v); }
; DI void gemm_tile(const GD& g, int pm, int pn, bf16_t* shm) {
;     ...
;             if (g.gnext) {
;               u32x2 o2; o2[0] = pk2(x.x * gn.x, x.y * gn.y); o2[1] = pk2(x.z * gn.z, x.w * gn.w);
;               *reinterpret_cast<u32x2*>(g.hbout + (long)grow * DM + gcol) = o2;
;               float sq = (x.x * x.x + x.y * x.y) + (x.z * x.z + x.w * x.w);
;               sq += shx_(sq, 1); sq += shx_(sq, 2); sq += shx_(sq, 4); sq += shx_(sq, 8);
;               if ((lane & 15) == 0) g.ss[(long)grow * 32 + pn * 4 + wc] = sq;
.LBB0_1281:
	v_mad_u64_u32 v[12:13], s[2:3], v10, s78, 0
	v_mov_b32_e32 v0, v13
	v_mad_u64_u32 v[14:15], s[2:3], v11, s78, v[0:1]
	v_mov_b32_e32 v13, v14
	v_lshl_add_u64 v[12:13], v[12:13], 2, s[34:35]
	s_waitcnt lgkmcnt(0)
	v_pk_add_f32 v[2:3], v[2:3], v[6:7]
	v_pk_add_f32 v[4:5], v[4:5], v[8:9]
	v_lshl_add_u64 v[12:13], v[94:95], 2, v[12:13]
	s_cmp_eq_u64 s[80:81], 0
	global_store_dwordx4 v[12:13], v[2:5], off
	s_cbranch_scc1 .LBB0_1285
	v_pk_mul_f32 v[12:13], v[18:19], v[2:3]
	v_pk_mul_f32 v[14:15], v[20:21], v[4:5]
	v_cvt_pk_bf16_f32 v12, v12, v13
	v_cvt_pk_bf16_f32 v13, v14, v15
	v_lshlrev_b64 v[14:15], 12, v[10:11]
	v_pk_mul_f32 v[2:3], v[2:3], v[2:3]
	v_pk_mul_f32 v[4:5], v[4:5], v[4:5]
	v_lshl_add_u64 v[14:15], s[20:21], 0, v[14:15]
	v_add_f32_e32 v0, v4, v5
	v_add_f32_e32 v2, v2, v3
	v_lshl_add_u64 v[14:15], v[94:95], 1, v[14:15]
	v_add_f32_e32 v0, v2, v0
	global_store_dwordx2 v[14:15], v[12:13], off
	s_nop 1
	v_mov_b32_dpp v2, v0 quad_perm:[1,0,3,2] row_mask:0xf bank_mask:0xf
	s_waitcnt lgkmcnt(0)
	v_add_f32_e32 v0, v0, v2
	s_nop 1
	v_mov_b32_dpp v2, v0 quad_perm:[2,3,0,1] row_mask:0xf bank_mask:0xf
	s_waitcnt lgkmcnt(0)
	v_add_f32_e32 v0, v0, v2
	s_nop 1
	v_mov_b32_dpp v2, v0 row_half_mirror row_mask:0xf bank_mask:0xf
	s_waitcnt lgkmcnt(0)
	v_add_f32_e32 v2, v0, v2
	s_nop 1
	v_mov_b32_dpp v3, v2 row_ror:8 row_mask:0xf bank_mask:0xf
	s_and_saveexec_b64 s[2:3], s[4:5]
	s_cbranch_execz .LBB0_1284
	v_lshlrev_b64 v[4:5], 7, v[10:11]
	v_lshl_add_u64 v[4:5], s[42:43], 0, v[4:5]
	v_lshl_add_u64 v[4:5], s[0:1], 2, v[4:5]
	v_lshlrev_b32_e32 v0, 2, v139
	v_lshl_add_u64 v[4:5], v[4:5], 0, v[0:1]
	s_waitcnt lgkmcnt(0)
	v_add_f32_e32 v0, v2, v3
	global_store_dword v[4:5], v0, off
